# v74 + attention unit prologue 5-hop bpermute max replaced by DPP/permlane16 max
# speedup vs baseline: 1.0090x; 1.0090x over previous
; __device__ __forceinline__ void attn_unit_pp(int b, int h, int qb, int par, const bf16_t* __restrict__ QBp, const bf16_t* __restrict__ KBp, const bf16_t* __restrict__ VBp, ...
;     ...
;   for (int d0 = 0; d0 < 4; ++d0) { const u32x4 w = __builtin_bit_cast(u32x4, qr[d0]);
; #pragma unroll
;     for (int e = 0; e < 4; ++e) { const float lo = __uint_as_float(w[e] << 16), hh = __uint_as_float(w[e] & 0xffff0000u); qn = fmaf(lo, lo, qn); qn = fmaf(hh, hh, qn); } }
;   { auto rr = __builtin_amdgcn_permlane32_swap(__float_as_uint(qn), __float_as_uint(qn), false, false); qn = __uint_as_float(rr[0]) + __uint_as_float(rr[1]); }
;   float sii = 0.f;
;   { const bf16_t* Kw = Kh + (size_t)(q0 + w4 * QBLK + r32) * LD + g * 64 + hi * 8;
; #pragma unroll
;     for (int d0 = 0; d0 < 4; ++d0) { const u32x4 wq = __builtin_bit_cast(u32x4, qr[d0]); const u32x4 wk = __builtin_bit_cast(u32x4, ld8(Kw + d0 * 16));
; #pragma unroll
;       for (int e = 0; e < 4; ++e) { sii = fmaf(__uint_as_float(wq[e] << 16), __uint_as_float(wk[e] << 16), sii); sii = fmaf(__uint_as_float(wq[e] & 0xffff0000u), __uint_as_float(wk[e] & 0xffff0000u), sii); } } }
;   { auto rr = __builtin_amdgcn_permlane32_swap(__float_as_uint(sii), __float_as_uint(sii), false, false); sii = __uint_as_float(rr[0]) + __uint_as_float(rr[1]); }
;   { const unsigned* nk = nrmk + ((size_t)((b * 8 + h) * 2 + g)) * 2; const float kn = __uint_as_float(__hip_atomic_load(nk, __ATOMIC_RELAXED, __HIP_MEMORY_SCOPE_AGENT)) + __uint_as_float(__hip_atomic_load(nk + 1, __ATOMIC_RELAXED, __HIP_MEMORY_SCOPE_AGENT));
;     qn = sqrtf(qn * kn) * 1.02f - sii; }
.LBB0_350:
	s_lshl_b64 s[0:1], s[16:17], 18
	s_lshl_b64 s[14:15], s[0:1], 1
	v_lshlrev_b32_e32 v8, 7, v5
	s_add_u32 s2, s42, s14
	s_addc_u32 s3, s43, s15
	v_lshlrev_b32_e32 v8, 1, v8
	v_mov_b32_e32 v9, v1
	v_lshlrev_b32_e32 v10, 3, v6
	v_lshl_add_u64 v[8:9], s[2:3], 0, v[8:9]
	v_lshl_add_u64 v[8:9], s[46:47], 1, v[8:9]
	v_lshlrev_b32_e32 v168, 1, v10
	v_mov_b32_e32 v169, v1
	v_lshl_add_u64 v[24:25], v[8:9], 0, v[168:169]
	global_load_dwordx4 v[8:11], v[24:25], off
	global_load_dwordx4 v[12:15], v[24:25], off offset:32
	global_load_dwordx4 v[20:23], v[24:25], off offset:64
	s_lshl_b32 s0, s16, 1
	global_load_dwordx4 v[24:27], v[24:25], off offset:96
	s_add_i32 s0, s38, s0
	s_ashr_i32 s1, s0, 31
	s_lshl_b64 s[0:1], s[0:1], 3
	s_add_u32 s0, s30, s0
	s_addc_u32 s1, s31, s1
	global_load_dword v57, v1, s[0:1] sc1
	global_load_dword v58, v1, s[0:1] offset:4 sc1
	s_lshl_b32 s98, s22, 1
	s_add_i32 s98, s98, s38
	v_lshl_or_b32 v204, s98, 6, v7
	v_lshlrev_b32_e32 v204, 8, v204
	v_add_u32_e32 v204, v204, v2
	global_load_dwordx4 v[146:149], v204, s[2:3]
	v_add_u32_e32 v208, 0x1000, v204
	global_load_dwordx4 v[150:153], v208, s[2:3]
	v_add_u32_e32 v209, 0x2000, v204
	global_load_dwordx4 v[154:157], v209, s[2:3]
	v_add_u32_e32 v210, 0x3000, v204
	global_load_dwordx4 v[158:161], v210, s[2:3]
	s_waitcnt vmcnt(13)
	v_lshlrev_b32_e32 v28, 16, v130
	v_and_b32_e32 v29, 0xffff0000, v130
	v_fma_f32 v30, v28, v28, 0
	v_fmac_f32_e32 v30, v29, v29
	v_lshlrev_b32_e32 v31, 16, v131
	v_and_b32_e32 v32, 0xffff0000, v131
	v_fmac_f32_e32 v30, v31, v31
	v_fmac_f32_e32 v30, v32, v32
	v_lshlrev_b32_e32 v33, 16, v132
	v_and_b32_e32 v34, 0xffff0000, v132
	v_fmac_f32_e32 v30, v33, v33
	v_fmac_f32_e32 v30, v34, v34
	v_lshlrev_b32_e32 v35, 16, v133
	v_and_b32_e32 v36, 0xffff0000, v133
	v_fmac_f32_e32 v30, v35, v35
	v_fmac_f32_e32 v30, v36, v36
	s_waitcnt vmcnt(12)
	v_lshlrev_b32_e32 v37, 16, v134
	v_and_b32_e32 v38, 0xffff0000, v134
	v_fmac_f32_e32 v30, v37, v37
	v_fmac_f32_e32 v30, v38, v38
	v_lshlrev_b32_e32 v39, 16, v135
	v_and_b32_e32 v40, 0xffff0000, v135
	v_fmac_f32_e32 v30, v39, v39
	v_fmac_f32_e32 v30, v40, v40
	v_lshlrev_b32_e32 v41, 16, v136
	v_and_b32_e32 v42, 0xffff0000, v136
	v_fmac_f32_e32 v30, v41, v41
	v_fmac_f32_e32 v30, v42, v42
	v_lshlrev_b32_e32 v43, 16, v137
	v_and_b32_e32 v44, 0xffff0000, v137
	v_fmac_f32_e32 v30, v43, v43
	v_fmac_f32_e32 v30, v44, v44
	s_waitcnt vmcnt(11)
	v_lshlrev_b32_e32 v45, 16, v138
	v_and_b32_e32 v46, 0xffff0000, v138
	v_fmac_f32_e32 v30, v45, v45
	v_fmac_f32_e32 v30, v46, v46
	v_lshlrev_b32_e32 v47, 16, v139
	v_and_b32_e32 v48, 0xffff0000, v139
	v_fmac_f32_e32 v30, v47, v47
	v_fmac_f32_e32 v30, v48, v48
	v_lshlrev_b32_e32 v49, 16, v140
	v_and_b32_e32 v50, 0xffff0000, v140
	v_fmac_f32_e32 v30, v49, v49
	v_fmac_f32_e32 v30, v50, v50
	v_lshlrev_b32_e32 v51, 16, v141
	v_and_b32_e32 v52, 0xffff0000, v141
	v_fmac_f32_e32 v30, v51, v51
	v_fmac_f32_e32 v30, v52, v52
	s_waitcnt vmcnt(10)
	v_lshlrev_b32_e32 v53, 16, v142
	v_and_b32_e32 v54, 0xffff0000, v142
	v_fmac_f32_e32 v30, v53, v53
	v_fmac_f32_e32 v30, v54, v54
	v_lshlrev_b32_e32 v55, 16, v143
	v_and_b32_e32 v56, 0xffff0000, v143
	v_fmac_f32_e32 v30, v55, v55
	v_fmac_f32_e32 v30, v56, v56
	v_lshlrev_b32_e32 v59, 16, v144
	v_and_b32_e32 v60, 0xffff0000, v144
	v_fmac_f32_e32 v30, v59, v59
	v_fmac_f32_e32 v30, v60, v60
	v_lshlrev_b32_e32 v61, 16, v145
	v_and_b32_e32 v62, 0xffff0000, v145
	v_fmac_f32_e32 v30, v61, v61
	v_fmac_f32_e32 v30, v62, v62
	v_mov_b32_e32 v63, v30
	s_nop 1
	v_permlane32_swap_b32_e32 v30, v63
	v_and_b32_e32 v186, 63, v4
	v_lshlrev_b32_e32 v187, 2, v186
	s_waitcnt vmcnt(9)
; __device__ __forceinline__ void attn_unit_pp(int b, int h, int qb, int par, const bf16_t* __restrict__ QBp, const bf16_t* __restrict__ KBp, const bf16_t* __restrict__ VBp, ...
;     ...
;     for (int d0 = 0; d0 < 4; ++d0) { const u32x4 wq = __builtin_bit_cast(u32x4, qr[d0]); const u32x4 wk = __builtin_bit_cast(u32x4, ld8(Kw + d0 * 16));
; #pragma unroll
;       for (int e = 0; e < 4; ++e) { sii = fmaf(__uint_as_float(wq[e] << 16), __uint_as_float(wk[e] << 16), sii); sii = fmaf(__uint_as_float(wq[e] & 0xffff0000u), __uint_as_float(wk[e] & 0xffff0000u), sii); } } }
;   { auto rr = __builtin_amdgcn_permlane32_swap(__float_as_uint(sii), __float_as_uint(sii), false, false); sii = __uint_as_float(rr[0]) + __uint_as_float(rr[1]); }
;   { const unsigned* nk = nrmk + ((size_t)((b * 8 + h) * 2 + g)) * 2; const float kn = __uint_as_float(__hip_atomic_load(nk, __ATOMIC_RELAXED, __HIP_MEMORY_SCOPE_AGENT)) + __uint_as_float(__hip_atomic_load(nk + 1, __ATOMIC_RELAXED, __HIP_MEMORY_SCOPE_AGENT));
;     qn = sqrtf(qn * kn) * 1.02f - sii; }
; #pragma unroll
;   for (int x = 1; x < 32; x <<= 1) qn = fmaxf(qn, __builtin_bit_cast(float, __builtin_amdgcn_ds_bpermute((lane ^ x) << 2, __builtin_bit_cast(int, qn))));
;   float* xb = (float*)(lds + 143360 + 128) + par * 16;
;   if (lane == 0) xb[wid] = qn;
	v_lshlrev_b32_e32 v64, 16, v8
	v_fma_f32 v28, v28, v64, 0
	v_and_b32_e32 v8, 0xffff0000, v8
	v_fmac_f32_e32 v28, v29, v8
	v_lshlrev_b32_e32 v8, 16, v9
	v_fmac_f32_e32 v28, v31, v8
	v_and_b32_e32 v8, 0xffff0000, v9
	v_fmac_f32_e32 v28, v32, v8
	v_lshlrev_b32_e32 v8, 16, v10
	v_fmac_f32_e32 v28, v33, v8
	v_and_b32_e32 v8, 0xffff0000, v10
	v_fmac_f32_e32 v28, v34, v8
	v_lshlrev_b32_e32 v8, 16, v11
	v_fmac_f32_e32 v28, v35, v8
	v_and_b32_e32 v8, 0xffff0000, v11
	v_fmac_f32_e32 v28, v36, v8
	s_waitcnt vmcnt(8)
	v_lshlrev_b32_e32 v8, 16, v12
	v_fmac_f32_e32 v28, v37, v8
	v_and_b32_e32 v8, 0xffff0000, v12
	v_fmac_f32_e32 v28, v38, v8
	v_lshlrev_b32_e32 v8, 16, v13
	v_fmac_f32_e32 v28, v39, v8
	v_and_b32_e32 v8, 0xffff0000, v13
	v_fmac_f32_e32 v28, v40, v8
	v_lshlrev_b32_e32 v8, 16, v14
	v_fmac_f32_e32 v28, v41, v8
	v_and_b32_e32 v8, 0xffff0000, v14
	v_fmac_f32_e32 v28, v42, v8
	v_lshlrev_b32_e32 v8, 16, v15
	v_fmac_f32_e32 v28, v43, v8
	v_and_b32_e32 v8, 0xffff0000, v15
	v_fmac_f32_e32 v28, v44, v8
	s_waitcnt vmcnt(7)
	v_lshlrev_b32_e32 v8, 16, v20
	v_fmac_f32_e32 v28, v45, v8
	v_and_b32_e32 v8, 0xffff0000, v20
	v_fmac_f32_e32 v28, v46, v8
	v_lshlrev_b32_e32 v8, 16, v21
	v_fmac_f32_e32 v28, v47, v8
	v_and_b32_e32 v8, 0xffff0000, v21
	v_fmac_f32_e32 v28, v48, v8
	v_lshlrev_b32_e32 v8, 16, v22
	v_fmac_f32_e32 v28, v49, v8
	v_and_b32_e32 v8, 0xffff0000, v22
	v_fmac_f32_e32 v28, v50, v8
	v_lshlrev_b32_e32 v8, 16, v23
	v_fmac_f32_e32 v28, v51, v8
	v_and_b32_e32 v8, 0xffff0000, v23
	v_fmac_f32_e32 v28, v52, v8
	s_waitcnt vmcnt(6)
	v_lshlrev_b32_e32 v8, 16, v24
	v_fmac_f32_e32 v28, v53, v8
	v_and_b32_e32 v8, 0xffff0000, v24
	v_fmac_f32_e32 v28, v54, v8
	v_lshlrev_b32_e32 v8, 16, v25
	v_fmac_f32_e32 v28, v55, v8
	v_and_b32_e32 v8, 0xffff0000, v25
	v_fmac_f32_e32 v28, v56, v8
	v_lshlrev_b32_e32 v8, 16, v26
	v_fmac_f32_e32 v28, v59, v8
	v_and_b32_e32 v8, 0xffff0000, v26
	v_fmac_f32_e32 v28, v60, v8
	v_lshlrev_b32_e32 v8, 16, v27
	v_fmac_f32_e32 v28, v61, v8
	v_and_b32_e32 v8, 0xffff0000, v27
	v_fmac_f32_e32 v28, v62, v8
	v_add_f32_e32 v8, v30, v63
	s_waitcnt vmcnt(4)
	v_add_f32_e32 v10, v57, v58
	v_mul_f32_e32 v8, v8, v10
	v_mul_f32_e32 v10, 0x4f800000, v8
	v_cmp_gt_f32_e32 vcc, s49, v8
	v_mov_b32_e32 v9, v28
	s_nop 1
	v_permlane32_swap_b32_e32 v28, v9
	v_cndmask_b32_e32 v8, v8, v10, vcc
	v_sqrt_f32_e32 v10, v8
	v_add_f32_e32 v9, v28, v9
	v_xor_b32_e32 v183, 4, v187
	v_xor_b32_e32 v182, 8, v187
	v_add_u32_e32 v11, -1, v10
	v_fma_f32 v12, -v11, v10, v8
	v_cmp_ge_f32_e64 s[0:1], 0, v12
	v_add_u32_e32 v12, 1, v10
	v_xor_b32_e32 v181, 16, v187
	v_cndmask_b32_e64 v11, v10, v11, s[0:1]
	v_fma_f32 v10, -v12, v10, v8
	v_cmp_lt_f32_e64 s[0:1], 0, v10
	v_xor_b32_e32 v180, 32, v187
	v_xor_b32_e32 v169, 64, v187
	v_cndmask_b32_e64 v10, v11, v12, s[0:1]
	v_mul_f32_e32 v11, 0x37800000, v10
	v_cndmask_b32_e32 v10, v10, v11, vcc
	v_cmp_class_f32_e32 vcc, v8, v176
	s_lshl_b32 s0, s82, 6
	s_and_b32 s0, s0, 64
	v_cndmask_b32_e32 v8, v10, v8, vcc
	v_fma_f32 v8, v8, s50, -v9
	s_add_i32 s11, s0, 0
	s_add_i32 s11, s11, 0x23080
	v_max_f32_dpp v8, v8, v8 quad_perm:[1,0,3,2] row_mask:0xf bank_mask:0xf
	v_cmp_eq_u32_e32 vcc, 0, v186
	s_nop 0
	v_max_f32_dpp v8, v8, v8 quad_perm:[2,3,0,1] row_mask:0xf bank_mask:0xf
	s_nop 1
	v_max_f32_dpp v8, v8, v8 row_half_mirror row_mask:0xf bank_mask:0xf
	s_nop 1
	v_max_f32_dpp v8, v8, v8 row_mirror row_mask:0xf bank_mask:0xf
	v_mov_b32_e32 v9, v8
	s_nop 1
	v_permlane16_swap_b32_e32 v9, v8
	v_max_f32_e32 v8, v8, v9
	s_and_saveexec_b64 s[0:1], vcc
	s_cbranch_execz .LBB0_352
	v_lshl_add_u32 v3, v3, 2, s11
	ds_write_b32 v3, v8
